# P1 tile loop without the per-tile epilogue alignment barrier pair (template's non-aligned form)
# speedup vs baseline: 1.0032x; 1.0032x over previous
.LBB0_131:
	ds_read_b128 v[152:155], v148
	ds_read_b128 v[156:159], v148 offset:1024
	ds_read_b128 v[160:163], v148 offset:2048
	ds_read_b128 v[164:167], v148 offset:3072
	ds_read_b128 v[168:171], v149
	ds_read_b128 v[172:175], v149 offset:1024
	ds_read_b128 v[176:179], v149 offset:2048
	ds_read_b128 v[180:183], v149 offset:3072
	s_add_u32 s20, s18, 0xfffc0080
	s_addc_u32 s21, s19, -1
	s_cmp_eq_u32 s46, 12
	s_cselect_b32 s23, s13, s21
	s_cselect_b32 s22, s42, s20
	s_cselect_b32 s21, s11, s45
	s_cselect_b32 s20, s43, s44
	s_add_i32 m0, s9, 0xc000
	ds_read_b128 v[184:187], v150
	ds_read_b128 v[188:191], v150 offset:1024
	ds_read_b128 v[192:195], v150 offset:2048
	ds_read_b128 v[196:199], v150 offset:3072
	ds_read_b128 v[200:203], v150 offset:4096
	ds_read_b128 v[204:207], v150 offset:5120
	ds_read_b128 v[208:211], v150 offset:6144
	ds_read_b128 v[212:215], v150 offset:7168
	global_load_lds_dwordx4 v136, s[18:19]
	s_add_i32 m0, s9, 0xe000
	s_nop 0
	global_load_lds_dwordx4 v138, s[18:19]
	s_waitcnt vmcnt(8)
	s_waitcnt lgkmcnt(0)
	s_barrier
	s_setprio 1
	s_waitcnt lgkmcnt(0)
	v_mfma_f32_16x16x32_bf16 v[124:127], v[152:155], v[184:187], v[124:127]
	v_mfma_f32_16x16x32_bf16 v[120:123], v[160:163], v[184:187], v[120:123]
	v_mfma_f32_16x16x32_bf16 v[116:119], v[152:155], v[192:195], v[116:119]
	v_mfma_f32_16x16x32_bf16 v[112:115], v[160:163], v[192:195], v[112:115]
	v_mfma_f32_16x16x32_bf16 v[100:103], v[152:155], v[200:203], v[100:103]
	v_mfma_f32_16x16x32_bf16 v[96:99], v[160:163], v[200:203], v[96:99]
	v_mfma_f32_16x16x32_bf16 v[84:87], v[152:155], v[208:211], v[84:87]
	v_mfma_f32_16x16x32_bf16 v[80:83], v[160:163], v[208:211], v[80:83]
	v_mfma_f32_16x16x32_bf16 v[124:127], v[156:159], v[188:191], v[124:127]
	v_mfma_f32_16x16x32_bf16 v[120:123], v[164:167], v[188:191], v[120:123]
	v_mfma_f32_16x16x32_bf16 v[116:119], v[156:159], v[196:199], v[116:119]
	v_mfma_f32_16x16x32_bf16 v[112:115], v[164:167], v[196:199], v[112:115]
	v_mfma_f32_16x16x32_bf16 v[100:103], v[156:159], v[204:207], v[100:103]
	v_mfma_f32_16x16x32_bf16 v[96:99], v[164:167], v[204:207], v[96:99]
	v_mfma_f32_16x16x32_bf16 v[84:87], v[156:159], v[212:215], v[84:87]
	v_mfma_f32_16x16x32_bf16 v[80:83], v[164:167], v[212:215], v[80:83]
	s_setprio 0
	s_setprio 1
	v_mfma_f32_16x16x32_bf16 v[108:111], v[168:171], v[184:187], v[108:111]
	v_mfma_f32_16x16x32_bf16 v[104:107], v[176:179], v[184:187], v[104:107]
	v_mfma_f32_16x16x32_bf16 v[92:95], v[168:171], v[192:195], v[92:95]
	v_mfma_f32_16x16x32_bf16 v[88:91], v[176:179], v[192:195], v[88:91]
	v_mfma_f32_16x16x32_bf16 v[76:79], v[168:171], v[200:203], v[76:79]
	v_mfma_f32_16x16x32_bf16 v[72:75], v[176:179], v[200:203], v[72:75]
	v_mfma_f32_16x16x32_bf16 v[68:71], v[168:171], v[208:211], v[68:71]
	v_mfma_f32_16x16x32_bf16 v[64:67], v[176:179], v[208:211], v[64:67]
	v_mfma_f32_16x16x32_bf16 v[108:111], v[172:175], v[188:191], v[108:111]
	v_mfma_f32_16x16x32_bf16 v[104:107], v[180:183], v[188:191], v[104:107]
	v_mfma_f32_16x16x32_bf16 v[92:95], v[172:175], v[196:199], v[92:95]
	v_mfma_f32_16x16x32_bf16 v[88:91], v[180:183], v[196:199], v[88:91]
	v_mfma_f32_16x16x32_bf16 v[76:79], v[172:175], v[204:207], v[76:79]
	v_mfma_f32_16x16x32_bf16 v[72:75], v[180:183], v[204:207], v[72:75]
	v_mfma_f32_16x16x32_bf16 v[68:71], v[172:175], v[212:215], v[68:71]
	v_mfma_f32_16x16x32_bf16 v[64:67], v[180:183], v[212:215], v[64:67]
	s_setprio 0
	s_barrier
	s_add_i32 s47, s38, s26
	s_mov_b32 m0, s47
	ds_read_b128 v[184:187], v150 offset:16384
	ds_read_b128 v[188:191], v150 offset:17408
	ds_read_b128 v[192:195], v150 offset:18432
	ds_read_b128 v[196:199], v150 offset:19456
	ds_read_b128 v[200:203], v150 offset:20480
	ds_read_b128 v[204:207], v150 offset:21504
	ds_read_b128 v[208:211], v150 offset:22528
	ds_read_b128 v[212:215], v150 offset:23552
	global_load_lds_dwordx4 v132, s[20:21]
	s_add_i32 m0, s47, 0x2000
	s_add_u32 s48, s20, 0x40000
	s_addc_u32 s49, s21, 0
	s_add_i32 s47, s39, s26
	global_load_lds_dwordx4 v128, s[20:21]
	s_mov_b32 m0, s47
	s_nop 0
	global_load_lds_dwordx4 v132, s[48:49]
	s_add_i32 m0, s47, 0x2000
	s_nop 0
	global_load_lds_dwordx4 v128, s[48:49]
	s_mov_b32 m0, s9
	s_nop 0
	global_load_lds_dwordx4 v134, s[22:23]
	s_mov_b32 m0, s29
	s_nop 0
	global_load_lds_dwordx4 v130, s[22:23]
	s_add_u32 s84, s20, s4
	s_addc_u32 s85, s21, s5
	s_add_u32 s86, s22, s4
	s_addc_u32 s87, s23, s5
	s_waitcnt vmcnt(8)
	s_waitcnt lgkmcnt(0)
	s_barrier
	s_setprio 1
	s_waitcnt lgkmcnt(0)
	v_mfma_f32_16x16x32_bf16 v[60:63], v[152:155], v[184:187], v[60:63]
	v_mfma_f32_16x16x32_bf16 v[56:59], v[160:163], v[184:187], v[56:59]
	v_mfma_f32_16x16x32_bf16 v[52:55], v[152:155], v[192:195], v[52:55]
	v_mfma_f32_16x16x32_bf16 v[48:51], v[160:163], v[192:195], v[48:51]
	v_mfma_f32_16x16x32_bf16 v[36:39], v[152:155], v[200:203], v[36:39]
	v_mfma_f32_16x16x32_bf16 v[32:35], v[160:163], v[200:203], v[32:35]
	v_mfma_f32_16x16x32_bf16 v[20:23], v[152:155], v[208:211], v[20:23]
	v_mfma_f32_16x16x32_bf16 v[16:19], v[160:163], v[208:211], v[16:19]
	v_mfma_f32_16x16x32_bf16 v[60:63], v[156:159], v[188:191], v[60:63]
	v_mfma_f32_16x16x32_bf16 v[56:59], v[164:167], v[188:191], v[56:59]
	v_mfma_f32_16x16x32_bf16 v[52:55], v[156:159], v[196:199], v[52:55]
	v_mfma_f32_16x16x32_bf16 v[48:51], v[164:167], v[196:199], v[48:51]
	v_mfma_f32_16x16x32_bf16 v[36:39], v[156:159], v[204:207], v[36:39]
	v_mfma_f32_16x16x32_bf16 v[32:35], v[164:167], v[204:207], v[32:35]
	v_mfma_f32_16x16x32_bf16 v[20:23], v[156:159], v[212:215], v[20:23]
	v_mfma_f32_16x16x32_bf16 v[16:19], v[164:167], v[212:215], v[16:19]
	s_setprio 0
	s_setprio 1
	v_mfma_f32_16x16x32_bf16 v[44:47], v[168:171], v[184:187], v[44:47]
	v_mfma_f32_16x16x32_bf16 v[40:43], v[176:179], v[184:187], v[40:43]
	v_mfma_f32_16x16x32_bf16 v[28:31], v[168:171], v[192:195], v[28:31]
	v_mfma_f32_16x16x32_bf16 v[24:27], v[176:179], v[192:195], v[24:27]
	v_mfma_f32_16x16x32_bf16 v[12:15], v[168:171], v[200:203], v[12:15]
	v_mfma_f32_16x16x32_bf16 v[8:11], v[176:179], v[200:203], v[8:11]
	v_mfma_f32_16x16x32_bf16 v[4:7], v[168:171], v[208:211], v[4:7]
	v_mfma_f32_16x16x32_bf16 v[0:3], v[176:179], v[208:211], v[0:3]
	v_mfma_f32_16x16x32_bf16 v[44:47], v[172:175], v[188:191], v[44:47]
	v_mfma_f32_16x16x32_bf16 v[40:43], v[180:183], v[188:191], v[40:43]
	v_mfma_f32_16x16x32_bf16 v[28:31], v[172:175], v[196:199], v[28:31]
	v_mfma_f32_16x16x32_bf16 v[24:27], v[180:183], v[196:199], v[24:27]
	v_mfma_f32_16x16x32_bf16 v[12:15], v[172:175], v[204:207], v[12:15]
	v_mfma_f32_16x16x32_bf16 v[8:11], v[180:183], v[204:207], v[8:11]
	v_mfma_f32_16x16x32_bf16 v[4:7], v[172:175], v[212:215], v[4:7]
	v_mfma_f32_16x16x32_bf16 v[0:3], v[180:183], v[212:215], v[0:3]
	s_setprio 0
	s_barrier
	s_add_i32 s47, 0, 0x18000
	v_add_u32_e32 v151, s47, v146
	s_add_i32 s48, 0, 0x1c000
	ds_read_b128 v[152:155], v151
	ds_read_b128 v[156:159], v151 offset:1024
	ds_read_b128 v[160:163], v151 offset:2048
	ds_read_b128 v[164:167], v151 offset:3072
	v_add_u32_e32 v151, s48, v146
	ds_read_b128 v[168:171], v151
	ds_read_b128 v[172:175], v151 offset:1024
	ds_read_b128 v[176:179], v151 offset:2048
	ds_read_b128 v[180:183], v151 offset:3072
	s_add_u32 s22, s22, 0x40000
	s_addc_u32 s23, s23, 0
	s_mov_b32 m0, s30
	ds_read_b128 v[184:187], v150 offset:32768
	ds_read_b128 v[188:191], v150 offset:33792
	ds_read_b128 v[192:195], v150 offset:34816
	ds_read_b128 v[196:199], v150 offset:35840
	ds_read_b128 v[200:203], v150 offset:36864
	ds_read_b128 v[204:207], v150 offset:37888
	ds_read_b128 v[208:211], v150 offset:38912
	ds_read_b128 v[212:215], v150 offset:39936
	global_load_lds_dwordx4 v134, s[22:23]
	s_mov_b32 m0, s31
	s_nop 0
	global_load_lds_dwordx4 v130, s[22:23]
	s_waitcnt vmcnt(8)
	s_waitcnt lgkmcnt(0)
	s_barrier
	s_setprio 1
	s_waitcnt lgkmcnt(0)
	v_mfma_f32_16x16x32_bf16 v[124:127], v[152:155], v[184:187], v[124:127]
	v_mfma_f32_16x16x32_bf16 v[120:123], v[160:163], v[184:187], v[120:123]
	v_mfma_f32_16x16x32_bf16 v[116:119], v[152:155], v[192:195], v[116:119]
	v_mfma_f32_16x16x32_bf16 v[112:115], v[160:163], v[192:195], v[112:115]
	v_mfma_f32_16x16x32_bf16 v[100:103], v[152:155], v[200:203], v[100:103]
	v_mfma_f32_16x16x32_bf16 v[96:99], v[160:163], v[200:203], v[96:99]
	v_mfma_f32_16x16x32_bf16 v[84:87], v[152:155], v[208:211], v[84:87]
	v_mfma_f32_16x16x32_bf16 v[80:83], v[160:163], v[208:211], v[80:83]
	v_mfma_f32_16x16x32_bf16 v[124:127], v[156:159], v[188:191], v[124:127]
	v_mfma_f32_16x16x32_bf16 v[120:123], v[164:167], v[188:191], v[120:123]
	v_mfma_f32_16x16x32_bf16 v[116:119], v[156:159], v[196:199], v[116:119]
	v_mfma_f32_16x16x32_bf16 v[112:115], v[164:167], v[196:199], v[112:115]
	v_mfma_f32_16x16x32_bf16 v[100:103], v[156:159], v[204:207], v[100:103]
	v_mfma_f32_16x16x32_bf16 v[96:99], v[164:167], v[204:207], v[96:99]
	v_mfma_f32_16x16x32_bf16 v[84:87], v[156:159], v[212:215], v[84:87]
	v_mfma_f32_16x16x32_bf16 v[80:83], v[164:167], v[212:215], v[80:83]
	s_setprio 0
	s_setprio 1
	v_mfma_f32_16x16x32_bf16 v[108:111], v[168:171], v[184:187], v[108:111]
	v_mfma_f32_16x16x32_bf16 v[104:107], v[176:179], v[184:187], v[104:107]
	v_mfma_f32_16x16x32_bf16 v[92:95], v[168:171], v[192:195], v[92:95]
	v_mfma_f32_16x16x32_bf16 v[88:91], v[176:179], v[192:195], v[88:91]
	v_mfma_f32_16x16x32_bf16 v[76:79], v[168:171], v[200:203], v[76:79]
	v_mfma_f32_16x16x32_bf16 v[72:75], v[176:179], v[200:203], v[72:75]
	v_mfma_f32_16x16x32_bf16 v[68:71], v[168:171], v[208:211], v[68:71]
	v_mfma_f32_16x16x32_bf16 v[64:67], v[176:179], v[208:211], v[64:67]
	v_mfma_f32_16x16x32_bf16 v[108:111], v[172:175], v[188:191], v[108:111]
	v_mfma_f32_16x16x32_bf16 v[104:107], v[180:183], v[188:191], v[104:107]
	v_mfma_f32_16x16x32_bf16 v[92:95], v[172:175], v[196:199], v[92:95]
	v_mfma_f32_16x16x32_bf16 v[88:91], v[180:183], v[196:199], v[88:91]
	v_mfma_f32_16x16x32_bf16 v[76:79], v[172:175], v[204:207], v[76:79]
	v_mfma_f32_16x16x32_bf16 v[72:75], v[180:183], v[204:207], v[72:75]
	v_mfma_f32_16x16x32_bf16 v[68:71], v[172:175], v[212:215], v[68:71]
	v_mfma_f32_16x16x32_bf16 v[64:67], v[180:183], v[212:215], v[64:67]
	s_setprio 0
	s_barrier
	s_add_i32 s22, s47, s26
	s_mov_b32 m0, s22
	ds_read_b128 v[184:187], v150 offset:49152
	ds_read_b128 v[188:191], v150 offset:50176
	ds_read_b128 v[192:195], v150 offset:51200
	ds_read_b128 v[196:199], v150 offset:52224
	ds_read_b128 v[200:203], v150 offset:53248
	ds_read_b128 v[204:207], v150 offset:54272
	ds_read_b128 v[208:211], v150 offset:55296
	ds_read_b128 v[212:215], v150 offset:56320
	global_load_lds_dwordx4 v132, s[84:85]
	s_add_i32 m0, s22, 0x2000
	s_add_u32 s20, s20, 0x40080
	s_addc_u32 s21, s21, 0
	s_add_i32 s22, s48, s26
	global_load_lds_dwordx4 v128, s[84:85]
	s_mov_b32 m0, s22
	s_nop 0
	global_load_lds_dwordx4 v132, s[20:21]
	s_add_i32 m0, s22, 0x2000
	s_nop 0
	global_load_lds_dwordx4 v128, s[20:21]
	s_mov_b32 m0, s34
	s_nop 0
	global_load_lds_dwordx4 v134, s[86:87]
	s_mov_b32 m0, s35
	s_nop 0
	global_load_lds_dwordx4 v130, s[86:87]
	s_waitcnt vmcnt(8)
	s_waitcnt lgkmcnt(0)
	s_barrier
	s_setprio 1
	s_waitcnt lgkmcnt(0)
	v_mfma_f32_16x16x32_bf16 v[60:63], v[152:155], v[184:187], v[60:63]
	v_mfma_f32_16x16x32_bf16 v[56:59], v[160:163], v[184:187], v[56:59]
	v_mfma_f32_16x16x32_bf16 v[52:55], v[152:155], v[192:195], v[52:55]
	v_mfma_f32_16x16x32_bf16 v[48:51], v[160:163], v[192:195], v[48:51]
	v_mfma_f32_16x16x32_bf16 v[36:39], v[152:155], v[200:203], v[36:39]
	v_mfma_f32_16x16x32_bf16 v[32:35], v[160:163], v[200:203], v[32:35]
	v_mfma_f32_16x16x32_bf16 v[20:23], v[152:155], v[208:211], v[20:23]
	v_mfma_f32_16x16x32_bf16 v[16:19], v[160:163], v[208:211], v[16:19]
	v_mfma_f32_16x16x32_bf16 v[60:63], v[156:159], v[188:191], v[60:63]
	v_mfma_f32_16x16x32_bf16 v[56:59], v[164:167], v[188:191], v[56:59]
	v_mfma_f32_16x16x32_bf16 v[52:55], v[156:159], v[196:199], v[52:55]
	v_mfma_f32_16x16x32_bf16 v[48:51], v[164:167], v[196:199], v[48:51]
	v_mfma_f32_16x16x32_bf16 v[36:39], v[156:159], v[204:207], v[36:39]
	v_mfma_f32_16x16x32_bf16 v[32:35], v[164:167], v[204:207], v[32:35]
	v_mfma_f32_16x16x32_bf16 v[20:23], v[156:159], v[212:215], v[20:23]
	v_mfma_f32_16x16x32_bf16 v[16:19], v[164:167], v[212:215], v[16:19]
	s_setprio 0
	s_setprio 1
	v_mfma_f32_16x16x32_bf16 v[44:47], v[168:171], v[184:187], v[44:47]
	v_mfma_f32_16x16x32_bf16 v[40:43], v[176:179], v[184:187], v[40:43]
	v_mfma_f32_16x16x32_bf16 v[28:31], v[168:171], v[192:195], v[28:31]
	v_mfma_f32_16x16x32_bf16 v[24:27], v[176:179], v[192:195], v[24:27]
	v_mfma_f32_16x16x32_bf16 v[12:15], v[168:171], v[200:203], v[12:15]
	v_mfma_f32_16x16x32_bf16 v[8:11], v[176:179], v[200:203], v[8:11]
	v_mfma_f32_16x16x32_bf16 v[4:7], v[168:171], v[208:211], v[4:7]
	v_mfma_f32_16x16x32_bf16 v[0:3], v[176:179], v[208:211], v[0:3]
	v_mfma_f32_16x16x32_bf16 v[44:47], v[172:175], v[188:191], v[44:47]
	v_mfma_f32_16x16x32_bf16 v[40:43], v[180:183], v[188:191], v[40:43]
	v_mfma_f32_16x16x32_bf16 v[28:31], v[172:175], v[196:199], v[28:31]
	v_mfma_f32_16x16x32_bf16 v[24:27], v[180:183], v[196:199], v[24:27]
	v_mfma_f32_16x16x32_bf16 v[12:15], v[172:175], v[204:207], v[12:15]
	v_mfma_f32_16x16x32_bf16 v[8:11], v[180:183], v[204:207], v[8:11]
	v_mfma_f32_16x16x32_bf16 v[4:7], v[172:175], v[212:215], v[4:7]
	v_mfma_f32_16x16x32_bf16 v[0:3], v[180:183], v[212:215], v[0:3]
	s_setprio 0
	s_barrier
	s_add_i32 s46, s46, 2
	s_add_u32 s18, s18, 0x100
	s_addc_u32 s19, s19, 0
	s_add_u32 s44, s44, 0x100
	s_addc_u32 s45, s45, 0
	s_cmp_gt_u32 s46, 13
	s_cbranch_scc0 .LBB0_131
	s_and_b64 vcc, exec, s[6:7]
	s_cbranch_vccz .LBB0_134

.LBB0_134:
	v_readlane_b32 s18, v254, 41
	v_lshl_add_u32 v151, s8, 8, v145
	v_lshl_or_b32 v152, s41, 8, v147
	v_readlane_b32 s19, v254, 42
	v_ashrrev_i32_e32 v153, 31, v152
	v_cvt_pk_bf16_f32 v68, v68, v69
	v_mov_b64_e32 v[154:155], s[18:19]
	v_cvt_pk_bf16_f32 v69, v70, v71
	v_cvt_pk_bf16_f32 v70, v64, v65
	v_add_u32_e32 v64, 0x80, v151
	v_mad_i64_i32 v[156:157], s[18:19], v151, s40, v[154:155]
	v_lshlrev_b64 v[152:153], 1, v[152:153]
	v_cvt_pk_bf16_f32 v108, v108, v109
	v_cvt_pk_bf16_f32 v109, v110, v111
	v_cvt_pk_bf16_f32 v110, v104, v105
	v_or_b32_e32 v104, 16, v151
	v_mad_i64_i32 v[64:65], s[18:19], v64, s40, v[154:155]
	v_cvt_pk_bf16_f32 v44, v44, v45
	v_cvt_pk_bf16_f32 v45, v46, v47
	v_cvt_pk_bf16_f32 v46, v40, v41
	v_add_u32_e32 v40, 0x90, v151
	v_lshl_add_u64 v[156:157], v[156:157], 0, v[152:153]
	v_cvt_pk_bf16_f32 v111, v106, v107
	v_mad_i64_i32 v[104:105], s[18:19], v104, s40, v[154:155]
	v_cvt_pk_bf16_f32 v92, v92, v93
	v_cvt_pk_bf16_f32 v93, v94, v95
	v_cvt_pk_bf16_f32 v94, v88, v89
	v_or_b32_e32 v88, 32, v151
	v_lshl_add_u64 v[64:65], v[64:65], 0, v[152:153]
	v_cvt_pk_bf16_f32 v47, v42, v43
	v_mad_i64_i32 v[40:41], s[18:19], v40, s40, v[154:155]
	v_cvt_pk_bf16_f32 v28, v28, v29
	v_cvt_pk_bf16_f32 v29, v30, v31
	v_cvt_pk_bf16_f32 v30, v24, v25
	v_add_u32_e32 v24, 0xa0, v151
	global_store_dwordx4 v[156:157], v[108:111], off offset:256
	v_cvt_pk_bf16_f32 v95, v90, v91
	v_mad_i64_i32 v[88:89], s[18:19], v88, s40, v[154:155]
	v_lshl_add_u64 v[108:109], v[104:105], 0, v[152:153]
	v_cvt_pk_bf16_f32 v76, v76, v77
	v_cvt_pk_bf16_f32 v77, v78, v79
	v_cvt_pk_bf16_f32 v78, v72, v73
	v_or_b32_e32 v72, 48, v151
	global_store_dwordx4 v[64:65], v[44:47], off offset:256
	v_cvt_pk_bf16_f32 v31, v26, v27
	v_mad_i64_i32 v[24:25], s[18:19], v24, s40, v[154:155]
	v_lshl_add_u64 v[44:45], v[40:41], 0, v[152:153]
	v_cvt_pk_bf16_f32 v12, v12, v13
	v_cvt_pk_bf16_f32 v13, v14, v15
	v_cvt_pk_bf16_f32 v14, v8, v9
	v_add_u32_e32 v8, 0xb0, v151
	global_store_dwordx4 v[108:109], v[92:95], off offset:256
	v_cvt_pk_bf16_f32 v79, v74, v75
	v_mad_i64_i32 v[72:73], s[18:19], v72, s40, v[154:155]
	v_lshl_add_u64 v[92:93], v[88:89], 0, v[152:153]
	global_store_dwordx4 v[44:45], v[28:31], off offset:256
	v_cvt_pk_bf16_f32 v15, v10, v11
	v_mad_i64_i32 v[8:9], s[18:19], v8, s40, v[154:155]
	v_lshl_add_u64 v[28:29], v[24:25], 0, v[152:153]
	v_cvt_pk_bf16_f32 v124, v124, v125
	v_cvt_pk_bf16_f32 v125, v126, v127
	v_cvt_pk_bf16_f32 v126, v120, v121
	v_cvt_pk_bf16_f32 v127, v122, v123
	v_cvt_pk_bf16_f32 v104, v116, v117
	v_cvt_pk_bf16_f32 v105, v118, v119
	v_cvt_pk_bf16_f32 v106, v112, v113
	v_cvt_pk_bf16_f32 v107, v114, v115
	v_cvt_pk_bf16_f32 v88, v100, v101
	v_cvt_pk_bf16_f32 v89, v102, v103
	v_cvt_pk_bf16_f32 v90, v96, v97
	v_cvt_pk_bf16_f32 v91, v98, v99
	global_store_dwordx4 v[92:93], v[76:79], off offset:256
	v_cvt_pk_bf16_f32 v74, v80, v81
	v_cvt_pk_bf16_f32 v75, v82, v83
	v_lshl_add_u64 v[76:77], v[72:73], 0, v[152:153]
	v_cvt_pk_bf16_f32 v72, v84, v85
	v_cvt_pk_bf16_f32 v73, v86, v87
	v_cvt_pk_bf16_f32 v71, v66, v67
	v_cvt_pk_bf16_f32 v60, v60, v61
	v_cvt_pk_bf16_f32 v61, v62, v63
	v_cvt_pk_bf16_f32 v62, v56, v57
	v_cvt_pk_bf16_f32 v63, v58, v59
	v_cvt_pk_bf16_f32 v40, v52, v53
	v_cvt_pk_bf16_f32 v41, v54, v55
	v_cvt_pk_bf16_f32 v42, v48, v49
	v_cvt_pk_bf16_f32 v43, v50, v51
	v_cvt_pk_bf16_f32 v24, v36, v37
	v_cvt_pk_bf16_f32 v25, v38, v39
	v_cvt_pk_bf16_f32 v26, v32, v33
	v_cvt_pk_bf16_f32 v27, v34, v35
	global_store_dwordx4 v[28:29], v[12:15], off offset:256
	v_cvt_pk_bf16_f32 v10, v16, v17
	v_cvt_pk_bf16_f32 v11, v18, v19
	v_lshl_add_u64 v[12:13], v[8:9], 0, v[152:153]
	v_cvt_pk_bf16_f32 v8, v20, v21
	v_cvt_pk_bf16_f32 v9, v22, v23
	v_cvt_pk_bf16_f32 v4, v4, v5
	v_cvt_pk_bf16_f32 v5, v6, v7
	v_cvt_pk_bf16_f32 v6, v0, v1
	v_cvt_pk_bf16_f32 v7, v2, v3
	s_andn2_b64 vcc, exec, s[0:1]
	s_mov_b64 s[0:1], -1
	global_store_dwordx4 v[156:157], v[124:127], off
	global_store_dwordx4 v[108:109], v[104:107], off
	global_store_dwordx4 v[92:93], v[88:91], off
	global_store_dwordx4 v[76:77], v[72:75], off
	global_store_dwordx4 v[76:77], v[68:71], off offset:256
	global_store_dwordx4 v[64:65], v[60:63], off
	global_store_dwordx4 v[44:45], v[40:43], off
	global_store_dwordx4 v[28:29], v[24:27], off
	global_store_dwordx4 v[12:13], v[8:11], off
	global_store_dwordx4 v[12:13], v[4:7], off offset:256
	s_cbranch_vccnz .LBB0_127
	s_andn2_b64 vcc, exec, s[2:3]
	s_cbranch_vccnz .LBB0_126

	s_branch .LBB0_126
.LBB0_137:
	s_and_b64 vcc, exec, s[6:7]
	s_cbranch_vccz .Lna_p1
	s_barrier
.Lna_p1:
	s_waitcnt vmcnt(0)
	v_readlane_b32 s24, v254, 43
	v_readlane_b32 s25, v254, 44
	s_barrier
